# v2 + P6 tile-start vmcnt(0) drain removed + mixer-B next-tile K/V loads issued before the step barrier
# baseline (speedup 1.0000x reference)
; #define LAS __attribute__((address_space(3)))
; template <int MASK, bool FIX> ...
;     const LAS unsigned char* kp = buf + (kvoff + r32) * KSTR + hi * 16;
;     f32x16 s = cinit;
; #pragma unroll
;     for (int d0 = 0; d0 < 4; ++d0) { const bf16x8 kf = *(const LAS bf16x8*)(kp + d0 * 32); s = __builtin_amdgcn_mfma_f32_32x32x16_bf16(kf, qf[d0], s, 0, 0, 0); }
;     const float NEG = -INFINITY;
;     if (MASK == 3) {
;         float bv[16];
; #pragma unroll
;         for (int r = 0; r < 16; ++r) bv[r] = rpbl[bidx0 + (r & 3) + 8 * (r >> 2)];
; #pragma unroll
;         for (int r = 0; r < 16; ++r) asm volatile("" : "+v"(bv[r]));
; #pragma unroll
;         for (int r = 0; r < 16; ++r) s[r] = ((vmask >> r) & 1u) ? (s[r] + bv[r]) : NEG;
;     }
; #pragma unroll
;     for (int r = 0; r < 16; ++r) {
;         const int kl0 = (r & 3) + 8 * (r >> 2);
;         if (MASK == 1) { if (kl0 + 4 * hi < r32) s[r] = NEG; }
;         if (MASK == 2) { if (kl0 + 4 * hi > r32) s[r] = NEG; }
;     }
;     if (!FIX) {
;         float mx = fmaxf(fmaxf(s[0], s[1]), fmaxf(s[2], s[3]));
; #pragma unroll
;         for (int r = 4; r < 16; r += 4) mx = fmaxf(mx, fmaxf(fmaxf(s[r], s[r + 1]), fmaxf(s[r + 2], s[r + 3])));
;         mx = swap_max(mx);
;         const float mnew = fmaxf(m, mx);
;         const float msafe = (mnew == NEG) ? 0.f : mnew;
;         if (__any(mnew > m)) {
;             const float alpha = __builtin_amdgcn_exp2f(m - msafe);
;             l *= alpha;
; #pragma unroll
;             for (int r = 0; r < 16; ++r) { o0[r] *= alpha; o1[r] *= alpha; }
;         }
;         m = mnew;
;         float ls = 0.f;
; #pragma unroll
;         for (int r = 0; r < 16; ++r) { s[r] = __builtin_amdgcn_exp2f(s[r] - msafe); ls += s[r]; }
;         l += ls;
;     } else {
; #pragma unroll
;         for (int r = 0; r < 16; ++r) s[r] = __builtin_amdgcn_exp2f(s[r]);
;         l += (((s[0] + s[1]) + (s[2] + s[3])) + ((s[4] + s[5]) + (s[6] + s[7]))) + (((s[8] + s[9]) + (s[10] + s[11])) + ((s[12] + s[13]) + (s[14] + s[15])));
;     }
;     u32x4 pw0, pw1;
;     pw0.x = cvtpk(s[0], s[1]); pw0.y = cvtpk(s[2], s[3]); pw0.z = cvtpk(s[4], s[5]); pw0.w = cvtpk(s[6], s[7]);
;     pw1.x = cvtpk(s[8], s[9]); pw1.y = cvtpk(s[10], s[11]); pw1.z = cvtpk(s[12], s[13]); pw1.w = cvtpk(s[14], s[15]);
;     const bf16x8 p0 = __builtin_bit_cast(bf16x8, pw0), p1 = __builtin_bit_cast(bf16x8, pw1);
.LBB0_727:
	s_bitcmp1_b32 s10, 0
	s_cselect_b32 s8, 0x4480, 0
	s_add_i32 s13, s48, s10
	v_add_u32_e32 v64, s10, v81
	s_add_i32 s55, s10, 1
	s_add_i32 s11, s54, s10
	s_add_i32 s14, s8, 0
	s_add_i32 s12, s13, 1
	v_cmp_gt_u32_e32 vcc, 8, v64
	v_cmp_lt_u32_e64 s[8:9], s13, v15
	s_cmp_lt_i32 s10, s49
	v_cndmask_b32_e32 v64, 0, v150, vcc
	v_cmp_gt_u32_e32 vcc, s13, v80
	s_cselect_b32 s10, s12, s11
	s_cselect_b32 s11, s51, s52
	s_and_b64 s[8:9], s[44:45], s[8:9]
	v_add_u32_e32 v65, s14, v178
	s_lshl_b32 s10, s10, 6
	s_or_b64 s[8:9], s[8:9], vcc
	v_add_u32_e32 v66, s14, v194
	s_waitcnt vmcnt(1)
	ds_write_b128 v65, v[96:99]
	s_waitcnt vmcnt(0)
	ds_write_b128 v66, v[100:103] offset:9216
	v_cndmask_b32_e64 v64, v64, 0, s[8:9]
	s_add_i32 s10, s10, s11
	v_add3_u32 v67, s14, v152, v189
	v_mad_i64_i32 v[240:241], s[8:9], s10, v156, v[104:105]
	s_nop 1
	global_load_dwordx4 v[96:99], v[240:241], off offset:2560
	global_load_dwordx4 v[100:103], v[240:241], off offset:3584
	s_waitcnt lgkmcnt(0)
	s_barrier
	v_and_b32_e32 v134, 1, v64
	v_and_b32_e32 v135, 2, v64
	v_and_b32_e32 v136, 4, v64
	v_and_b32_e32 v137, 8, v64
	v_and_b32_e32 v138, 16, v64
	v_and_b32_e32 v139, 32, v64
	v_and_b32_e32 v140, 64, v64
	v_and_b32_e32 v141, 0x80, v64
	v_and_b32_e32 v142, 0x100, v64
	v_and_b32_e32 v143, 0x200, v64
	v_and_b32_e32 v144, 0x400, v64
	v_and_b32_e32 v145, 0x800, v64
	v_and_b32_e32 v146, 0x1000, v64
	v_and_b32_e32 v147, 0x2000, v64
	v_and_b32_e32 v158, 0x4000, v64
	v_and_b32_e32 v159, 0x8000, v64
	ds_read_b128 v[84:87], v67
	ds_read_b128 v[88:91], v67 offset:32
	ds_read_b128 v[106:109], v67 offset:64
	ds_read_b128 v[110:113], v67 offset:96
	ds_read2_b32 v[118:119], v82 offset1:1
	ds_read2_b32 v[120:121], v82 offset0:2 offset1:3
	ds_read2_b32 v[122:123], v82 offset0:8 offset1:9
	ds_read2_b32 v[124:125], v82 offset0:10 offset1:11
	ds_read2_b32 v[126:127], v82 offset0:16 offset1:17
	ds_read2_b32 v[128:129], v82 offset0:18 offset1:19
	ds_read2_b32 v[130:131], v82 offset0:24 offset1:25
	s_waitcnt lgkmcnt(13)
	ds_read2_b32 v[132:133], v82 offset0:26 offset1:27
	v_add3_u32 v68, s14, v190, v153
	v_add3_u32 v83, v68, v191, v192
	s_waitcnt lgkmcnt(11)
	v_mfma_f32_32x32x16_bf16 v[64:79], v[84:87], v[2:5], v[16:31]
	s_waitcnt lgkmcnt(7)
	s_waitcnt lgkmcnt(6)
	s_waitcnt lgkmcnt(5)
	s_waitcnt lgkmcnt(4)
	v_mfma_f32_32x32x16_bf16 v[64:79], v[88:91], v[6:9], v[64:79]
	s_waitcnt lgkmcnt(3)
	s_waitcnt lgkmcnt(2)
	s_waitcnt lgkmcnt(1)
	v_mfma_f32_32x32x16_bf16 v[64:79], v[106:109], v[10:13], v[64:79]
	s_waitcnt lgkmcnt(0)
	ds_read_b64_tr_b16 v[84:85], v83 offset:9216
	v_cmp_ne_u32_e32 vcc, 0, v135
	v_cmp_ne_u32_e64 s[8:9], 0, v136
	v_cmp_ne_u32_e64 s[10:11], 0, v137
	v_cmp_ne_u32_e64 s[12:13], 0, v138
	v_mfma_f32_32x32x16_bf16 v[64:79], v[110:113], v[92:95], v[64:79]
	v_cmp_ne_u32_e64 s[14:15], 0, v139
	v_cmp_ne_u32_e64 s[16:17], 0, v140
	v_cmp_ne_u32_e64 s[18:19], 0, v141
	v_cmp_eq_u32_e64 s[38:39], 1, v134
	ds_read_b64_tr_b16 v[86:87], v83 offset:9728
	ds_read_b64_tr_b16 v[88:89], v83 offset:10240
	ds_read_b64_tr_b16 v[90:91], v83 offset:10752
	ds_read_b64_tr_b16 v[106:107], v83 offset:13376
	ds_read_b64_tr_b16 v[108:109], v83 offset:13888
	ds_read_b64_tr_b16 v[114:115], v83 offset:14400
	ds_read_b64_tr_b16 v[116:117], v83 offset:14912
	v_cmp_ne_u32_e64 s[20:21], 0, v142
	v_cmp_ne_u32_e64 s[24:25], 0, v144
	v_add_f32_e32 v64, v118, v64
	v_add_f32_e32 v65, v119, v65
	v_add_f32_e32 v66, v120, v66
	v_add_f32_e32 v67, v121, v67
	v_add_f32_e32 v68, v122, v68
	v_add_f32_e32 v69, v123, v69
	v_add_f32_e32 v70, v124, v70
	v_add_f32_e32 v71, v125, v71
	v_add_f32_e32 v72, v126, v72
	v_add_f32_e32 v74, v128, v74
	v_add_f32_e32 v76, v130, v76
	v_cmp_ne_u32_e64 s[28:29], 0, v146
	v_add_f32_e32 v83, v132, v78
	v_cndmask_b32_e64 v64, v157, v64, s[38:39]
	v_cndmask_b32_e32 v65, v157, v65, vcc
	v_cndmask_b32_e64 v66, v157, v66, s[8:9]
	v_cndmask_b32_e64 v67, v157, v67, s[10:11]
	v_cndmask_b32_e64 v78, v157, v68, s[12:13]
	v_cndmask_b32_e64 v69, v157, v69, s[14:15]
	v_cndmask_b32_e64 v110, v157, v70, s[16:17]
	v_cndmask_b32_e64 v71, v157, v71, s[18:19]
	v_cndmask_b32_e64 v111, v157, v72, s[20:21]
	v_cndmask_b32_e64 v113, v157, v74, s[24:25]
	v_cndmask_b32_e64 v118, v157, v76, s[28:29]
	v_exp_f32_e32 v68, v64
	v_exp_f32_e32 v70, v65
	v_exp_f32_e32 v72, v66
	v_exp_f32_e32 v74, v67
	v_exp_f32_e32 v76, v78
	v_exp_f32_e32 v78, v69
	v_exp_f32_e32 v110, v110
	v_exp_f32_e32 v112, v71
	v_cvt_pk_bf16_f32 v64, v68, v70
	v_cvt_pk_bf16_f32 v65, v72, v74
	v_cvt_pk_bf16_f32 v66, v76, v78
	v_cvt_pk_bf16_f32 v67, v110, v112
	v_add_f32_e32 v73, v127, v73
	v_cmp_ne_u32_e64 s[22:23], 0, v143
	s_waitcnt lgkmcnt(6)
	v_mfma_f32_32x32x16_bf16 v[32:47], v[84:87], v[64:67], v[32:47]
	v_add_f32_e32 v75, v129, v75
	v_cmp_ne_u32_e64 s[26:27], 0, v145
	v_add_f32_e32 v77, v131, v77
	v_cmp_ne_u32_e64 s[30:31], 0, v147
	v_cmp_ne_u32_e64 s[34:35], 0, v158
	v_add_f32_e32 v79, v133, v79
	v_cmp_ne_u32_e64 s[36:37], 0, v159
	s_waitcnt lgkmcnt(2)
	v_mfma_f32_32x32x16_bf16 v[48:63], v[106:109], v[64:67], v[48:63]
	v_cndmask_b32_e64 v73, v157, v73, s[22:23]
	v_cndmask_b32_e64 v75, v157, v75, s[26:27]
	v_cndmask_b32_e64 v119, v157, v77, s[30:31]
	v_cndmask_b32_e64 v83, v157, v83, s[34:35]
	v_cndmask_b32_e64 v84, v157, v79, s[36:37]
	v_exp_f32_e32 v69, v111
	v_exp_f32_e32 v71, v73
	v_exp_f32_e32 v73, v113
	v_exp_f32_e32 v75, v75
	v_exp_f32_e32 v77, v118
	v_exp_f32_e32 v79, v119
	v_exp_f32_e32 v111, v83
	v_exp_f32_e32 v113, v84
	v_cvt_pk_bf16_f32 v64, v69, v71
	v_cvt_pk_bf16_f32 v65, v73, v75
	v_cvt_pk_bf16_f32 v66, v77, v79
	v_cvt_pk_bf16_f32 v67, v111, v113
	v_pk_add_f32 v[68:69], v[68:69], v[70:71]
	v_pk_add_f32 v[70:71], v[72:73], v[74:75]
	v_mfma_f32_32x32x16_bf16 v[32:47], v[88:91], v[64:67], v[32:47]
	v_add_f32_e64 v68, v68, v70
	v_add_f32_e64 v69, v69, v71
	s_mov_b32 s10, s55
	v_add_u32_e32 v82, 0x7c, v82
	s_cmp_eq_u32 s42, s55
	s_waitcnt lgkmcnt(0)
	v_mfma_f32_32x32x16_bf16 v[48:63], v[114:117], v[64:67], v[48:63]
	v_add_f32_e64 v64, v76, v78
	v_add_f32_e64 v65, v77, v79
	v_add_f32_e64 v66, v110, v112
	v_add_f32_e64 v67, v111, v113
	v_add_f32_e64 v64, v64, v66
	v_add_f32_e64 v65, v65, v67
	v_pk_add_f32 v[64:65], v[68:69], v[64:65]
	s_nop 0
	v_add_f32_e32 v64, v64, v65
	v_add_f32_e32 v0, v0, v64
	s_cbranch_scc0 .LBB0_727
	s_add_i32 s11, s49, 1
	s_branch .LBB0_730

; template <bool MASKED>
; __device__ __forceinline__ void tile64(const LAS unsigned char* buf, const bf16x8 (&qf)[4], f32x16& o0, f32x16& o1, float& l, int lane, int r32, int hi, const f32x16& cinit,
;                                        int a0, int b0, int a1, int b1) {
;     ...
;     const LAS unsigned char* kp = buf + r32 * KSTR + hi * 16;
;     const LAS unsigned char* vp = buf + K_BYTES + (4 * hi + ((lane & 15) >> 2)) * 64 + 32 * ((lane >> 4) & 1) + 8 * (lane & 3);
;     const int dq = 4 * hi - r32; const float NEG = -INFINITY;
;     bf16x8 kf0[4], kf1[4];
; #pragma unroll
;     for (int d0 = 0; d0 < 4; ++d0) { kf0[d0] = *(const LAS bf16x8*)(kp + d0 * 32); kf1[d0] = *(const LAS bf16x8*)(kp + 32 * KSTR + d0 * 32); }
;     T64_SB();
;     f32x16 s0 = cinit, s1 = cinit;
; #pragma unroll
;     for (int d0 = 0; d0 < 4; ++d0) s0 = __builtin_amdgcn_mfma_f32_32x32x16_bf16(kf0[d0], qf[d0], s0, 0, 0, 0);
;     s16x4 va[2][8];
; #pragma unroll
;     for (int dh = 0; dh < 2; ++dh)
; #pragma unroll
;         for (int j = 0; j < 8; ++j) va[dh][j] = vtr(vp + dh * V_HALF + j * 512);
;     T64_SB();
; #pragma unroll
;     for (int d0 = 0; d0 < 4; ++d0) {
;         s1 = __builtin_amdgcn_mfma_f32_32x32x16_bf16(kf1[d0], qf[d0], s1, 0, 0, 0);
; #pragma unroll
;         for (int r = 4 * d0; r < 4 * d0 + 4; ++r) { if (MASKED) { const int t = (r & 3) + 8 * (r >> 2) + dq; if (t < a0 || t > b0) s0[r] = NEG; } s0[r] = __builtin_amdgcn_exp2f(s0[r]); }
;         T64_SB();
;     }
;     u32x4 w00, w01;
;     w00.x = cvtpk(s0[0], s0[1]); w00.y = cvtpk(s0[2], s0[3]); w00.z = cvtpk(s0[4], s0[5]); w00.w = cvtpk(s0[6], s0[7]);
;     w01.x = cvtpk(s0[8], s0[9]); w01.y = cvtpk(s0[10], s0[11]); w01.z = cvtpk(s0[12], s0[13]); w01.w = cvtpk(s0[14], s0[15]);
;     const bf16x8 p00 = __builtin_bit_cast(bf16x8, w00), p01 = __builtin_bit_cast(bf16x8, w01);
;     l += (((s0[0] + s0[1]) + (s0[2] + s0[3])) + ((s0[4] + s0[5]) + (s0[6] + s0[7]))) + (((s0[8] + s0[9]) + (s0[10] + s0[11])) + ((s0[12] + s0[13]) + (s0[14] + s0[15])));
;     ...
;     T64_SB();
;     o0 = __builtin_amdgcn_mfma_f32_32x32x16_bf16(T64_VF(0, 0), p00, o0, 0, 0, 0); T64_EXP1(0);  T64_SB();
;     o1 = __builtin_amdgcn_mfma_f32_32x32x16_bf16(T64_VF(1, 0), p00, o1, 0, 0, 0); T64_EXP1(4);  T64_SB();
;     o0 = __builtin_amdgcn_mfma_f32_32x32x16_bf16(T64_VF(0, 1), p01, o0, 0, 0, 0); T64_EXP1(8);  T64_SB();
.LBB0_731:
	s_bitcmp1_b32 s11, 0
	s_cselect_b32 s12, 0x4480, 0
	s_add_i32 s9, s11, 1
	s_add_i32 s14, s12, 0
	s_cmp_lt_i32 s9, s8
	s_cselect_b64 s[12:13], -1, 0
	s_and_b64 vcc, s[12:13], exec
	s_cselect_b32 s11, s9, s11
	s_cmp_gt_i32 s11, s49
	s_cselect_b32 s12, s50, s48
	s_cselect_b32 s13, s52, s51
	s_add_i32 s12, s12, s11
	v_add_u32_e32 v64, s14, v178
	s_lshl_b32 s11, s12, 6
	v_add_u32_e32 v65, s14, v194
	s_waitcnt vmcnt(1)
	ds_write_b128 v64, v[96:99]
	s_waitcnt vmcnt(0)
	ds_write_b128 v65, v[100:103] offset:9216
	s_add_i32 s11, s11, s13
	v_mad_i64_i32 v[240:241], s[12:13], s11, v156, v[104:105]
	s_nop 1
	global_load_dwordx4 v[96:99], v[240:241], off offset:2560
	global_load_dwordx4 v[100:103], v[240:241], off offset:3584
	s_waitcnt lgkmcnt(0)
	s_barrier
	v_add3_u32 v76, s14, v179, v189
	ds_read_b128 v[64:67], v76
	ds_read_b128 v[68:71], v76 offset:32
	ds_read_b128 v[106:109], v76 offset:4608
	ds_read_b128 v[110:113], v76 offset:4640
	ds_read_b128 v[72:75], v76 offset:64
	ds_read_b128 v[114:117], v76 offset:96
	ds_read_b128 v[118:121], v76 offset:4672
	ds_read_b128 v[122:125], v76 offset:4704
	v_add3_u32 v126, s14, v190, v193
	s_waitcnt lgkmcnt(7)
	v_mfma_f32_32x32x16_bf16 v[76:91], v[64:67], v[2:5], v[16:31]
	v_add3_u32 v64, v126, v191, v192
	ds_read_b64_tr_b16 v[126:127], v64 offset:9216
	ds_read_b64_tr_b16 v[128:129], v64 offset:9728
	ds_read_b64_tr_b16 v[130:131], v64 offset:10240
	ds_read_b64_tr_b16 v[132:133], v64 offset:10752
	ds_read_b64_tr_b16 v[134:135], v64 offset:11264
	ds_read_b64_tr_b16 v[136:137], v64 offset:11776
	ds_read_b64_tr_b16 v[138:139], v64 offset:12288
	ds_read_b64_tr_b16 v[140:141], v64 offset:12800
	ds_read_b64_tr_b16 v[142:143], v64 offset:13376
	ds_read_b64_tr_b16 v[144:145], v64 offset:13888
	ds_read_b64_tr_b16 v[158:159], v64 offset:14400
	ds_read_b64_tr_b16 v[160:161], v64 offset:14912
	ds_read_b64_tr_b16 v[162:163], v64 offset:15424
	ds_read_b64_tr_b16 v[164:165], v64 offset:15936
	ds_read_b64_tr_b16 v[166:167], v64 offset:16448
	ds_read_b64_tr_b16 v[168:169], v64 offset:16960
	s_waitcnt lgkmcnt(14)
	v_mfma_f32_32x32x16_bf16 v[76:91], v[68:71], v[6:9], v[76:91]
	v_mfma_f32_32x32x16_bf16 v[76:91], v[72:75], v[10:13], v[76:91]
	v_mfma_f32_32x32x16_bf16 v[76:91], v[114:117], v[92:95], v[76:91]
	s_nop 11
	v_exp_f32_e32 v114, v76
	v_exp_f32_e32 v116, v77
	v_exp_f32_e32 v146, v78
	v_exp_f32_e32 v170, v79
	v_mfma_f32_32x32x16_bf16 v[64:79], v[106:109], v[2:5], v[16:31]
	v_exp_f32_e32 v106, v80
	v_exp_f32_e32 v108, v81
	v_exp_f32_e32 v172, v82
	v_exp_f32_e32 v174, v83
	v_mfma_f32_32x32x16_bf16 v[64:79], v[110:113], v[6:9], v[64:79]
	v_exp_f32_e32 v110, v84
	v_exp_f32_e32 v112, v85
	v_exp_f32_e32 v182, v86
	v_exp_f32_e32 v184, v87
	v_mfma_f32_32x32x16_bf16 v[64:79], v[118:121], v[10:13], v[64:79]
	v_exp_f32_e32 v88, v88
	v_exp_f32_e32 v118, v89
	v_exp_f32_e32 v90, v90
	v_exp_f32_e32 v120, v91
	v_mfma_f32_32x32x16_bf16 v[64:79], v[122:125], v[92:95], v[64:79]
	v_cvt_pk_bf16_f32 v80, v114, v116
	v_cvt_pk_bf16_f32 v81, v146, v170
	v_cvt_pk_bf16_f32 v82, v106, v108
	v_cvt_pk_bf16_f32 v83, v172, v174
	v_cvt_pk_bf16_f32 v84, v110, v112
	v_cvt_pk_bf16_f32 v85, v182, v184
	v_cvt_pk_bf16_f32 v86, v88, v118
	v_cvt_pk_bf16_f32 v87, v90, v120
	v_mfma_f32_32x32x16_bf16 v[32:47], v[126:129], v[80:83], v[32:47]
	s_nop 2
	v_exp_f32_e32 v115, v64
	v_exp_f32_e32 v117, v65
	v_exp_f32_e32 v147, v66
	v_exp_f32_e32 v171, v67
	s_waitcnt lgkmcnt(6)
	v_mfma_f32_32x32x16_bf16 v[48:63], v[142:145], v[80:83], v[48:63]
	v_exp_f32_e32 v107, v68
	v_exp_f32_e32 v109, v69
	v_exp_f32_e32 v173, v70
	v_exp_f32_e32 v175, v71
	v_mfma_f32_32x32x16_bf16 v[32:47], v[130:133], v[84:87], v[32:47]
	v_exp_f32_e32 v111, v72
	v_exp_f32_e32 v113, v73
	v_exp_f32_e32 v183, v74
	v_exp_f32_e32 v185, v75
	s_waitcnt lgkmcnt(4)
	v_mfma_f32_32x32x16_bf16 v[48:63], v[158:161], v[84:87], v[48:63]
	v_exp_f32_e32 v89, v76
	v_exp_f32_e32 v119, v77
	v_exp_f32_e32 v91, v78
	v_exp_f32_e32 v121, v79
	v_cvt_pk_bf16_f32 v64, v115, v117
	v_cvt_pk_bf16_f32 v65, v147, v171
	v_cvt_pk_bf16_f32 v66, v107, v109
	v_cvt_pk_bf16_f32 v67, v173, v175
	v_cvt_pk_bf16_f32 v68, v111, v113
	v_cvt_pk_bf16_f32 v69, v183, v185
	v_mfma_f32_32x32x16_bf16 v[32:47], v[134:137], v[64:67], v[32:47]
	v_cvt_pk_bf16_f32 v70, v89, v119
	v_cvt_pk_bf16_f32 v71, v91, v121
	v_add_f32_e64 v72, v106, v108
	v_add_f32_e64 v73, v107, v109
	v_add_f32_e64 v74, v172, v174
	v_add_f32_e64 v75, v173, v175
	v_pk_add_f32 v[76:77], v[110:111], v[112:113]
	v_pk_add_f32 v[78:79], v[182:183], v[184:185]
	v_pk_add_f32 v[80:81], v[88:89], v[118:119]
	s_waitcnt lgkmcnt(2)
	v_mfma_f32_32x32x16_bf16 v[48:63], v[162:165], v[64:67], v[48:63]
	v_add_f32_e64 v64, v114, v116
	v_add_f32_e64 v65, v115, v117
	v_add_f32_e64 v66, v146, v170
	v_add_f32_e64 v67, v147, v171
	v_add_f32_e64 v82, v90, v120
	v_add_f32_e64 v83, v91, v121
	v_pk_add_f32 v[64:65], v[64:65], v[66:67]
	v_pk_add_f32 v[66:67], v[72:73], v[74:75]
	v_pk_add_f32 v[72:73], v[76:77], v[78:79]
	v_pk_add_f32 v[74:75], v[80:81], v[82:83]
	v_mfma_f32_32x32x16_bf16 v[32:47], v[138:141], v[68:71], v[32:47]
	v_add_f32_e64 v64, v64, v66
	v_add_f32_e64 v65, v65, v67
	v_add_f32_e64 v66, v72, v74
	v_add_f32_e64 v67, v73, v75
	s_mov_b32 s11, s9
	v_pk_add_f32 v[64:65], v[64:65], v[66:67]
	s_nop 0
	v_add_f32_e32 v0, v0, v64
	v_add_f32_e32 v0, v0, v65
	s_waitcnt lgkmcnt(0)
	v_mfma_f32_32x32x16_bf16 v[48:63], v[166:169], v[68:71], v[48:63]
	s_cbranch_vccnz .LBB0_731

; template <class Epi, class Sched>
; __device__ __forceinline__ void gemm_phase(PG8_LAS unsigned char* lds, PG8_LAS unsigned char* ldx, const Gemm g, const Sched& S, const Epi& E, const int wid) {
;     ...
;         const bool has_next = S.next(ui + 1, nxt);
;         const char* nA = has_next ? (const char*)g.A + (size_t)nxt.pm * tstep : cA; const char* nB = has_next ? (const char*)g.Bt + (size_t)nxt.pn * tstep : cB;
;     ...
; #pragma unroll
;         for (int a = 0; a < 2; ++a)
; #pragma unroll
;             for (int b = 0; b < 2; ++b)
; #pragma unroll
;                 for (int m = 0; m < 4; ++m)
; #pragma unroll
;                     for (int n = 0; n < 2; ++n) acc[a][b][m][n] = (f32x4){0.f, 0.f, 0.f, 0.f};
;         cur = nxt; cA = nA; cB = nB; ++ui;
;         E.prefetch(pre, cur, wr, wc, fr, fq);
.LBB0_943:
	s_ashr_i32 s19, s18, 31
	s_lshl_b64 s[20:21], s[18:19], 19
	s_add_u32 s20, s1, s20
	s_addc_u32 s21, s34, s21
	s_and_b64 s[22:23], s[2:3], exec
	s_cselect_b32 s19, s21, s27
	s_cselect_b32 s54, s20, s26
	s_ashr_i32 s17, s16, 31
	s_lshl_b64 s[22:23], s[16:17], 19
	s_add_u32 s22, s35, s22
	s_addc_u32 s23, s36, s23
	s_and_b64 s[30:31], s[2:3], exec
	s_cselect_b32 s17, s23, s29
	s_cselect_b32 s55, s22, s28
	s_add_u32 s26, s26, 0x40080
	s_addc_u32 s27, s27, 0
	s_add_u32 s56, s28, 0x100
	v_mov_b32_e32 v16, 0
	s_addc_u32 s57, s29, 0
	s_mov_b32 s58, -2
	v_mov_b32_e32 v17, v16
	v_mov_b32_e32 v18, v16
	v_mov_b32_e32 v19, v16
	v_mov_b32_e32 v20, v16
	v_mov_b32_e32 v21, v16
	v_mov_b32_e32 v22, v16
	v_mov_b32_e32 v23, v16
	v_mov_b32_e32 v32, v16
	v_mov_b32_e32 v33, v16
	v_mov_b32_e32 v34, v16
	v_mov_b32_e32 v35, v16
	v_mov_b32_e32 v36, v16
	v_mov_b32_e32 v37, v16
	v_mov_b32_e32 v38, v16
	v_mov_b32_e32 v39, v16
	v_mov_b32_e32 v48, v16
	v_mov_b32_e32 v49, v16
	v_mov_b32_e32 v50, v16
	v_mov_b32_e32 v51, v16
	v_mov_b32_e32 v52, v16
	v_mov_b32_e32 v53, v16
	v_mov_b32_e32 v54, v16
	v_mov_b32_e32 v55, v16
	v_mov_b32_e32 v64, v16
	v_mov_b32_e32 v65, v16
	v_mov_b32_e32 v66, v16
	v_mov_b32_e32 v67, v16
	v_mov_b32_e32 v68, v16
	v_mov_b32_e32 v69, v16
	v_mov_b32_e32 v70, v16
	v_mov_b32_e32 v71, v16
	v_mov_b32_e32 v24, v16
	v_mov_b32_e32 v25, v16
	v_mov_b32_e32 v26, v16
	v_mov_b32_e32 v27, v16
	v_mov_b32_e32 v28, v16
	v_mov_b32_e32 v29, v16
	v_mov_b32_e32 v30, v16
	v_mov_b32_e32 v31, v16
	v_mov_b32_e32 v40, v16
	v_mov_b32_e32 v41, v16
	v_mov_b32_e32 v42, v16
	v_mov_b32_e32 v43, v16
	v_mov_b32_e32 v44, v16
	v_mov_b32_e32 v45, v16
	v_mov_b32_e32 v46, v16
	v_mov_b32_e32 v47, v16
	v_mov_b32_e32 v56, v16
	v_mov_b32_e32 v57, v16
	v_mov_b32_e32 v58, v16
	v_mov_b32_e32 v59, v16
	v_mov_b32_e32 v60, v16
	v_mov_b32_e32 v61, v16
	v_mov_b32_e32 v62, v16
	v_mov_b32_e32 v63, v16
	v_mov_b32_e32 v72, v16
	v_mov_b32_e32 v73, v16
	v_mov_b32_e32 v74, v16
	v_mov_b32_e32 v75, v16
	v_mov_b32_e32 v76, v16
	v_mov_b32_e32 v77, v16
	v_mov_b32_e32 v78, v16
	v_mov_b32_e32 v79, v16
	v_mov_b32_e32 v80, v16
	v_mov_b32_e32 v81, v16
	v_mov_b32_e32 v82, v16
	v_mov_b32_e32 v83, v16
	v_mov_b32_e32 v84, v16
	v_mov_b32_e32 v85, v16
	v_mov_b32_e32 v86, v16
	v_mov_b32_e32 v87, v16
	v_mov_b32_e32 v96, v16
	v_mov_b32_e32 v97, v16
	v_mov_b32_e32 v98, v16
	v_mov_b32_e32 v99, v16
	v_mov_b32_e32 v100, v16
	v_mov_b32_e32 v101, v16
	v_mov_b32_e32 v102, v16
	v_mov_b32_e32 v103, v16
	v_mov_b32_e32 v112, v16
	v_mov_b32_e32 v113, v16
	v_mov_b32_e32 v114, v16
	v_mov_b32_e32 v115, v16
	v_mov_b32_e32 v116, v16
	v_mov_b32_e32 v117, v16
	v_mov_b32_e32 v118, v16
	v_mov_b32_e32 v119, v16
	v_mov_b32_e32 v128, v16
	v_mov_b32_e32 v129, v16
	v_mov_b32_e32 v130, v16
	v_mov_b32_e32 v131, v16
	v_mov_b32_e32 v132, v16
	s_waitcnt lgkmcnt(0)
	v_mov_b32_e32 v133, v16
	v_mov_b32_e32 v134, v16
	v_mov_b32_e32 v135, v16
	v_mov_b32_e32 v88, v16
	v_mov_b32_e32 v89, v16
	v_mov_b32_e32 v90, v16
	v_mov_b32_e32 v91, v16
	v_mov_b32_e32 v92, v16
	v_mov_b32_e32 v93, v16
	v_mov_b32_e32 v94, v16
	v_mov_b32_e32 v95, v16
	v_mov_b32_e32 v104, v16
	v_mov_b32_e32 v105, v16
	v_mov_b32_e32 v106, v16
	v_mov_b32_e32 v107, v16
	v_mov_b32_e32 v108, v16
	v_mov_b32_e32 v109, v16
	v_mov_b32_e32 v110, v16
	v_mov_b32_e32 v111, v16
	v_mov_b32_e32 v120, v16
	v_mov_b32_e32 v121, v16
	v_mov_b32_e32 v122, v16
	v_mov_b32_e32 v123, v16
	v_mov_b32_e32 v124, v16
	v_mov_b32_e32 v125, v16
	v_mov_b32_e32 v126, v16
	v_mov_b32_e32 v127, v16
	v_mov_b32_e32 v136, v16
	v_mov_b32_e32 v137, v16
	v_mov_b32_e32 v138, v16
	v_mov_b32_e32 v139, v16
	v_mov_b32_e32 v140, v16
	v_mov_b32_e32 v141, v16
	v_mov_b32_e32 v142, v16
	v_mov_b32_e32 v143, v16
